# C loop c6: counted lgkm waits, single tile-end barrier, staging without nops
# baseline (speedup 1.0000x reference)
; template <int MODE>
; DI void attn_unit(unsigned char* lds, const AttnParams& ap, int b, int h, int qb, int tid) {
;     ...
;   const int wave = tid >> 6, lane = tid & 63, r32 = lane & 31, hi = lane >> 5, bh = b * 4 + h;
;   constexpr int qcol0 = (MODE == 0) ? C_AQ : (MODE == 1) ? C_CQ : C_DQ, kcol0 = (MODE == 0) ? C_AK : (MODE == 1) ? C_CK : C_DK, ycol0 = (MODE == 0) ? 0 : (MODE == 1) ? 512 : 768;
;   const bf16_t* Vt = ap.Vt + (size_t)((MODE == 0) ? 0 : (MODE == 1) ? 2 : 3) * T_ * 256;
;   const size_t tokb = (size_t)b * SEQ;
;   const int qpos = qb * 256 + wave * 32 + r32, cw = qb * 4 + (wave >> 1);
;   bf16x8 qf[4];
;   { const bf16_t* qp = ap.P + (tokb + qpos) * PLD + qcol0 + h * 64 + 8 * hi;
; #pragma unroll
;     for (int ks = 0; ks < 4; ++ks) qf[ks] = *(const bf16x8*)(qp + 16 * ks); }
;   bf16_t* Ks0 = (bf16_t*)lds; bf16_t* Vs0 = Ks0 + NCH * 64 * 72; volatile int* flags = (volatile int*)(lds + 2 * NCH * 64 * 72 * 2);
;   const int jhi = 4 * qb + 3, jlo = (MODE == 0) ? ((4 * qb - 8 > 0) ? 4 * qb - 8 : 0) : 0, ntiles = jhi - jlo + 1;
;   const int lrow = tid >> 3, lch = tid & 7;
;   const bf16_t* kg = ap.P + (tokb + lrow) * PLD + kcol0 + h * 64 + 8 * lch;
;   const bf16_t* vg = Vt + (size_t)bh * 256 * 4096 + lrow * 64 + 8 * lch;
;   const int j0 = (MODE == 2) ? jhi : jlo;
;   u32x4 kreg[NCH], vreg[NCH];
; #pragma unroll
;   for (int c = 0; c < NCH; ++c) { const int jc = (MODE == 2) ? j0 - c : j0 + c; kreg[c] = *(const u32x4*)(kg + (size_t)jc * 64 * PLD); vreg[c] = *(const u32x4*)(vg + (size_t)jc * 4096); }
;   f32x16 O0[2], O1[2]; float l0 = 0.f, l1 = 0.f, cum = 0.f;
; #pragma unroll
;   for (int eb = 0; eb < 2; ++eb) { O0[eb] = splat16(0.f); O1[eb] = splat16(0.f); }
;   bool wdone = false;
;   if (MODE == 2 && D_EARLY) { if (tid < 8) flags[tid] = 0; }
;   for (int n = 0; n < ntiles; n += NCH) {
;     const int jb = (MODE == 2) ? jhi - n : jlo + n;
;     __syncthreads();
;     if (MODE == 2 && D_EARLY) { int alld = 1;
; #pragma unroll
;       for (int w = 0; w < 8; ++w) alld &= flags[w];
;       if (alld) break; }
; #pragma unroll
;     for (int c = 0; c < NCH; ++c) { *(u32x4*)(Ks0 + (c * 64 + lrow) * 72 + 8 * lch) = kreg[c]; *(u32x4*)(Vs0 + (c * 64 + lrow) * 72 + 8 * lch) = vreg[c]; }
;     __syncthreads();
;     if (n + NCH < ntiles) {
; #pragma unroll
.LBB0_845:
	v_readlane_b32 s0, v255, 51
	v_readlane_b32 s1, v255, 52
	s_andn2_saveexec_b64 s[6:7], s[0:1]
	s_cbranch_execz .LBB0_853
	v_mov_b32_e32 v1, v156
	v_readlane_b32 s0, v255, 25
	v_ashrrev_i32_e32 v2, 1, v1
	v_and_b32_e32 v2, 0xffffffe0, v2
	v_and_b32_e32 v7, 31, v1
	v_lshl_add_u32 v2, v0, 8, v2
	v_or_b32_e32 v2, v2, v7
	v_lshlrev_b32_e32 v32, 14, v4
	v_ashrrev_i32_e32 v3, 31, v2
	v_readlane_b32 s1, v255, 26
	v_lshl_add_u64 v[134:135], v[2:3], 0, v[32:33]
	v_bfe_u32 v47, v1, 5, 1
	v_mov_b64_e32 v[2:3], s[0:1]
	v_mad_u64_u32 v[8:9], s[0:1], v134, s82, v[2:3]
	v_mad_i32_i24 v9, v135, s82, v9
	v_lshlrev_b32_e32 v10, 7, v5
	v_mov_b32_e32 v11, v33
	v_lshl_add_u64 v[8:9], v[8:9], 0, v[10:11]
	v_lshlrev_b32_e32 v132, 4, v47
	v_mov_b32_e32 v133, v33
	v_lshl_add_u64 v[8:9], v[8:9], 0, v[132:133]
	v_ashrrev_i32_e32 v14, 3, v1
	global_load_dwordx4 v[112:115], v[8:9], off offset:3584
	global_load_dwordx4 v[42:45], v[8:9], off offset:3616
	global_load_dwordx4 v[38:41], v[8:9], off offset:3648
	global_load_dwordx4 v[34:37], v[8:9], off offset:3680
	v_add_u32_e32 v8, v14, v32
	v_mad_i64_i32 v[2:3], s[0:1], v8, s82, v[2:3]
	v_lshlrev_b32_e32 v8, 4, v1
	v_and_b32_e32 v32, 0x70, v8
	v_lshlrev_b32_e32 v8, 21, v5
	v_readlane_b32 s0, v255, 41
	v_lshl_add_u64 v[2:3], v[2:3], 0, v[10:11]
	v_lshl_or_b32 v8, v4, 23, v8
	v_mov_b32_e32 v9, v33
	v_readlane_b32 s1, v255, 42
	v_lshlrev_b32_e32 v12, 6, v14
	v_lshl_add_u64 v[2:3], v[2:3], 0, v[32:33]
	v_lshl_add_u64 v[10:11], s[0:1], 0, v[8:9]
	v_ashrrev_i32_e32 v13, 31, v12
	s_movk_i32 s0, 0x1000
	v_lshlrev_b64 v[12:13], 1, v[12:13]
	v_add_co_u32_e32 v2, vcc, s0, v2
	v_lshl_add_u64 v[10:11], v[10:11], 0, v[12:13]
	s_nop 0
	v_addc_co_u32_e32 v3, vcc, 0, v3, vcc
	v_lshl_add_u64 v[10:11], v[10:11], 0, v[32:33]
	global_load_dwordx4 v[120:123], v[2:3], off
	global_load_dwordx4 v[116:119], v[10:11], off
	v_ashrrev_i32_e32 v157, 7, v1
	v_lshlrev_b32_e32 v0, 2, v0
	v_mul_lo_u32 v1, v14, s68
	v_or_b32_e32 v12, v12, v32
	v_readlane_b32 s0, v255, 47
	v_add_u32_e32 v191, v157, v0
	v_add3_u32 v190, 0, v32, v1
	v_or_b32_e32 v192, 3, v0
	v_lshl_add_u64 v[0:1], v[12:13], 0, v[8:9]
	v_readlane_b32 s1, v255, 48
	v_add_u16_e32 v2, -1, v6
	v_and_b32_e32 v2, 3, v2
	v_lshl_add_u64 v[136:137], s[0:1], 0, v[0:1]
	v_mad_i64_i32 v[0:1], s[0:1], v14, s82, 0
	s_mov_b32 s0, 0x6880000
	s_nop 0
	v_mad_u64_u32 v[0:1], s[0:1], v4, s0, v[0:1]
	v_lshlrev_b32_e32 v2, 7, v2
	v_mov_b32_e32 v3, v33
	v_lshl_add_u64 v[0:1], v[0:1], 0, v[2:3]
	v_readlane_b32 s0, v255, 49
	v_lshl_add_u64 v[0:1], v[0:1], 0, v[32:33]
	v_readlane_b32 s1, v255, 50
	v_mov_b32_e32 v14, v33
	v_mov_b32_e32 v15, v33
	v_lshlrev_b32_e32 v46, 6, v5
	v_mul_u32_u24_e32 v155, 0x90, v7
	v_lshl_add_u64 v[138:139], s[0:1], 0, v[0:1]
	v_mov_b32_e32 v32, v33
	v_mov_b32_e32 v0, v33
	v_mov_b32_e32 v1, v33
	v_mov_b32_e32 v2, v33
	v_mov_b32_e32 v4, v33
	v_mov_b32_e32 v5, v33
	v_mov_b32_e32 v6, v33
	v_mov_b32_e32 v7, v33
	v_mov_b32_e32 v8, v33
	v_mov_b32_e32 v10, v33
	v_mov_b32_e32 v11, v33
	v_mov_b32_e32 v12, v33
	v_mov_b32_e32 v13, v33
	v_mov_b64_e32 v[78:79], v[14:15]
	v_mov_b64_e32 v[30:31], v[14:15]
	v_mov_b64_e32 v[94:95], v[14:15]
	s_mov_b32 s4, 0
	v_add_u32_e32 v133, 0, v132
	s_mov_b64 s[0:1], 0
	v_mov_b64_e32 v[76:77], v[12:13]
	v_mov_b64_e32 v[74:75], v[10:11]
	v_mov_b64_e32 v[72:73], v[8:9]
	v_mov_b64_e32 v[70:71], v[6:7]
	v_mov_b64_e32 v[68:69], v[4:5]
	v_mov_b64_e32 v[66:67], v[2:3]
	v_mov_b64_e32 v[64:65], v[0:1]
	v_mov_b64_e32 v[28:29], v[12:13]
	v_mov_b64_e32 v[26:27], v[10:11]
	v_mov_b64_e32 v[24:25], v[8:9]
	v_mov_b64_e32 v[22:23], v[6:7]
	v_mov_b64_e32 v[20:21], v[4:5]
	v_mov_b64_e32 v[18:19], v[2:3]
	v_mov_b64_e32 v[16:17], v[0:1]
	v_mov_b64_e32 v[92:93], v[12:13]
	v_mov_b64_e32 v[90:91], v[10:11]
	v_mov_b64_e32 v[88:89], v[8:9]
	v_mov_b64_e32 v[86:87], v[6:7]
	v_mov_b64_e32 v[84:85], v[4:5]
	v_mov_b64_e32 v[82:83], v[2:3]
	v_mov_b64_e32 v[80:81], v[0:1]
	v_mov_b64_e32 v[140:141], v[32:33]
	v_readfirstlane_b32 s5, v191
	v_readfirstlane_b32 s8, v192
	v_readfirstlane_b32 s2, v138
	v_readfirstlane_b32 s3, v139
	v_readfirstlane_b32 s10, v136
	v_readfirstlane_b32 s11, v137
	v_readfirstlane_b32 s0, v156
	v_and_b32_e32 v204, 7, v156
	v_bfe_u32 v205, v156, 4, 3
	v_xor_b32_e32 v205, v204, v205
	v_sub_u32_e32 v206, v205, v204
	v_lshlrev_b32_e32 v206, 4, v206
	v_subrev_u32_e32 v32, s2, v138
	v_subrev_u32_e32 v157, s10, v136
	v_add_u32_e32 v32, v32, v206
	v_add_u32_e32 v157, v157, v206
	v_lshrrev_b32_e32 v207, 3, v156
	v_lshlrev_b32_e32 v207, 7, v207
	v_lshl_add_u32 v207, v205, 4, v207
	v_and_b32_e32 v204, 31, v156
	v_bfe_u32 v205, v156, 5, 1
	v_bfe_u32 v206, v156, 1, 3
	v_lshlrev_b32_e32 v204, 7, v204
	v_add_u32_e32 v146, 0, v205
	v_xor_b32_e32 v146, v146, v206
	v_lshl_add_u32 v146, v146, 4, v204
	v_add_u32_e32 v147, 2, v205
	v_xor_b32_e32 v147, v147, v206
	v_lshl_add_u32 v147, v147, 4, v204
	v_add_u32_e32 v148, 4, v205
	v_xor_b32_e32 v148, v148, v206
	v_lshl_add_u32 v148, v148, 4, v204
	v_add_u32_e32 v149, 6, v205
	v_xor_b32_e32 v149, v149, v206
	v_lshl_add_u32 v149, v149, 4, v204
	s_lshr_b32 s0, s0, 6
	s_lshl_b32 s0, s0, 10
	s_add_i32 m0, s0, 16384
	s_add_i32 s4, s4, 1
	global_load_lds_dwordx4 v32, s[2:3]
	s_add_i32 m0, s0, 24576
	s_add_u32 s2, s2, 0x68800
	s_addc_u32 s3, s3, 0
	global_load_lds_dwordx4 v157, s[10:11]
	s_add_u32 s10, s10, 0x2000
	s_addc_u32 s11, s11, 0
	s_waitcnt vmcnt(2)
	ds_write_b128 v207, v[120:123]
	ds_write_b128 v207, v[116:119] offset:8192
	s_waitcnt vmcnt(0) lgkmcnt(0)
	s_barrier
	ds_read_b128 v[166:169], v146
	ds_read_b128 v[170:173], v147
	v_mov_b32_e32 v158, 0
	v_mov_b32_e32 v159, 0
	v_mov_b32_e32 v160, 0
	v_mov_b32_e32 v161, 0
	v_mov_b32_e32 v162, 0
	v_mov_b32_e32 v163, 0
	v_mov_b32_e32 v164, 0
	v_mov_b32_e32 v165, 0
	v_mov_b32_e32 v150, 0
	v_mov_b32_e32 v151, 0
	s_mov_b32 s4, 0
	s_waitcnt lgkmcnt(0)
	v_mfma_f32_32x32x16_bf16 v[96:111], v[166:169], v[112:115], v[48:63]
	v_mfma_f32_32x32x16_bf16 v[96:111], v[170:173], v[42:45], v[96:111]
	ds_read_b128 v[166:169], v148
	ds_read_b128 v[170:173], v149
	v_mov_b32_e32 v174, 0
	v_mov_b32_e32 v175, 0
	v_mov_b32_e32 v176, 0
	v_mov_b32_e32 v177, 0
	v_mov_b32_e32 v178, 0
	v_mov_b32_e32 v179, 0
	v_mov_b32_e32 v180, 0
	v_mov_b32_e32 v181, 0
	v_mov_b32_e32 v182, 0
	v_mov_b32_e32 v183, 0
	v_mov_b32_e32 v184, 0
	v_mov_b32_e32 v185, 0
	v_mov_b32_e32 v186, 0
	v_mov_b32_e32 v187, 0
	v_mov_b32_e32 v188, 0
	v_mov_b32_e32 v189, 0
; DI float ex2(float x) { return __builtin_amdgcn_exp2f(x); }
; #define MFMA32(a, b, c) __builtin_amdgcn_mfma_f32_32x32x16_bf16((a), (b), (c), 0, 0, 0)
; template <int MODE>
; DI void attn_unit(unsigned char* lds, const AttnParams& ap, int b, int h, int qb, int tid) {
;     ...
;   for (int n = 0; n < ntiles; n += NCH) {
;     const int jb = (MODE == 2) ? jhi - n : jlo + n;
;     __syncthreads();
;     if (MODE == 2 && D_EARLY) { int alld = 1;
; #pragma unroll
;       for (int w = 0; w < 8; ++w) alld &= flags[w];
;       if (alld) break; }
; #pragma unroll
;     for (int c = 0; c < NCH; ++c) { *(u32x4*)(Ks0 + (c * 64 + lrow) * 72 + 8 * lch) = kreg[c]; *(u32x4*)(Vs0 + (c * 64 + lrow) * 72 + 8 * lch) = vreg[c]; }
;     __syncthreads();
;     if (n + NCH < ntiles) {
; #pragma unroll
;       for (int c = 0; c < NCH; ++c) { const int jn = (MODE == 2) ? jb - NCH - c : jb + NCH + c; kreg[c] = *(const u32x4*)(kg + (size_t)jn * 64 * PLD); vreg[c] = *(const u32x4*)(vg + (size_t)jn * 4096); } }
;     ...
;       for (int kh = 0; kh < 2; ++kh) {
;         const bf16_t* kb = Ks + (32 * kh + r32) * 72 + 8 * hi;
;         bf16x8 p0[2], p1[2];
;         { f32x16 s0 = splat16(ap.negM);
;           s0 = MFMA32(*(const bf16x8*)(kb), qf[0], s0); s0 = MFMA32(*(const bf16x8*)(kb + 16), qf[1], s0);
; #pragma unroll
;           for (int i = 0; i < 16; ++i) { s0[i] = ex2(s0[i]); l0 += s0[i]; }
;           p0[0] = pack8(s0, 0); p0[1] = pack8(s0, 1); }
;         { f32x16 s1 = splat16(ap.negM);
;           s1 = MFMA32(*(const bf16x8*)(kb + 32), qf[2], s1); s1 = MFMA32(*(const bf16x8*)(kb + 48), qf[3], s1);
; #pragma unroll
;           for (int i = 0; i < 16; ++i) { s1[i] = ex2(s1[i]); l1 += s1[i]; }
;           p1[0] = pack8(s1, 0); p1[1] = pack8(s1, 1); }
; #pragma unroll
;         for (int kk = 0; kk < 2; ++kk) {
; #pragma unroll
;           for (int eb = 0; eb < 2; ++eb) { const bf16_t* vb = Vs + (32 * eb + r32) * 72 + 32 * kh + 16 * kk + 8 * hi; const bf16x8 vf = *(const bf16x8*)vb;
;             O0[eb] = MFMA32(vf, p0[kk], O0[eb]); O1[eb] = MFMA32(vf, p1[kk], O1[eb]); } }
.Lc_tile_ph0:
	s_add_i32 m0, s0, 32768
	s_add_i32 s4, s4, 1
	global_load_lds_dwordx4 v32, s[2:3]
	s_add_i32 m0, s0, 40960
	s_add_u32 s2, s2, 0x68800
	s_addc_u32 s3, s3, 0
	global_load_lds_dwordx4 v157, s[10:11]
	s_add_u32 s10, s10, 0x2000
	s_addc_u32 s11, s11, 0
	s_waitcnt lgkmcnt(0)
	v_mfma_f32_32x32x16_bf16 v[116:131], v[166:169], v[38:41], v[48:63]
	v_exp_f32_e32 v96, v96
	v_exp_f32_e32 v97, v97
	v_exp_f32_e32 v98, v98
	v_exp_f32_e32 v99, v99
	v_mfma_f32_32x32x16_bf16 v[116:131], v[170:173], v[34:37], v[116:131]
	v_exp_f32_e32 v100, v100
	v_exp_f32_e32 v101, v101
	v_exp_f32_e32 v102, v102
	v_exp_f32_e32 v103, v103
	ds_read_b128 v[166:169], v146 offset:4096
	ds_read_b128 v[170:173], v147 offset:4096
	v_mfma_f32_32x32x16_bf16 v[80:95], v[174:177], v[158:161], v[80:95]
	v_exp_f32_e32 v104, v104
	v_exp_f32_e32 v105, v105
	v_add_f32_e32 v141, v141, v96
	v_add_f32_e32 v150, v150, v97
	v_add_f32_e32 v141, v141, v98
	v_add_f32_e32 v150, v150, v99
	v_mfma_f32_32x32x16_bf16 v[16:31], v[182:185], v[158:161], v[16:31]
	v_exp_f32_e32 v106, v106
	v_exp_f32_e32 v107, v107
	v_cvt_pk_bf16_f32 v158, v96, v97
	v_cvt_pk_bf16_f32 v159, v98, v99
	v_add_f32_e32 v141, v141, v100
	v_add_f32_e32 v150, v150, v101
	v_mfma_f32_32x32x16_bf16 v[80:95], v[178:181], v[162:165], v[80:95]
	v_exp_f32_e32 v108, v108
	v_exp_f32_e32 v109, v109
	v_cvt_pk_bf16_f32 v160, v100, v101
	v_cvt_pk_bf16_f32 v161, v102, v103
	v_add_f32_e32 v141, v141, v102
	v_add_f32_e32 v150, v150, v103
	v_mfma_f32_32x32x16_bf16 v[16:31], v[186:189], v[162:165], v[16:31]
	ds_read_b128 v[174:177], v146 offset:8192
	ds_read_b128 v[178:181], v147 offset:8192
	ds_read_b128 v[182:185], v146 offset:12288
	ds_read_b128 v[186:189], v147 offset:12288
	v_exp_f32_e32 v110, v110
	v_exp_f32_e32 v111, v111
	v_add_f32_e32 v141, v141, v104
	v_add_f32_e32 v150, v150, v105
	v_add_f32_e32 v141, v141, v106
	v_add_f32_e32 v150, v150, v107
	v_add_f32_e32 v141, v141, v108
	v_add_f32_e32 v150, v150, v109
	v_cvt_pk_bf16_f32 v162, v104, v105
	v_cvt_pk_bf16_f32 v163, v106, v107
	v_cvt_pk_bf16_f32 v164, v108, v109
	v_add_f32_e32 v141, v141, v110
	v_add_f32_e32 v150, v150, v111
	v_cvt_pk_bf16_f32 v165, v110, v111
	s_waitcnt lgkmcnt(4)
	v_mfma_f32_32x32x16_bf16 v[96:111], v[166:169], v[112:115], v[48:63]
	v_exp_f32_e32 v116, v116
	v_exp_f32_e32 v117, v117
	v_exp_f32_e32 v118, v118
	v_exp_f32_e32 v119, v119
	v_mfma_f32_32x32x16_bf16 v[96:111], v[170:173], v[42:45], v[96:111]
	v_exp_f32_e32 v120, v120
	v_exp_f32_e32 v121, v121
	v_exp_f32_e32 v122, v122
	v_exp_f32_e32 v123, v123
	ds_read_b128 v[166:169], v148 offset:4096
	ds_read_b128 v[170:173], v149 offset:4096
	s_waitcnt lgkmcnt(2)
	v_mfma_f32_32x32x16_bf16 v[64:79], v[174:177], v[158:161], v[64:79]
	v_exp_f32_e32 v124, v124
	v_exp_f32_e32 v125, v125
	v_add_f32_e32 v140, v140, v116
	v_add_f32_e32 v151, v151, v117
	v_add_f32_e32 v140, v140, v118
	v_add_f32_e32 v151, v151, v119
	v_mfma_f32_32x32x16_bf16 v[0:15], v[182:185], v[158:161], v[0:15]
	v_exp_f32_e32 v126, v126
	v_exp_f32_e32 v127, v127
	v_cvt_pk_bf16_f32 v158, v116, v117
	v_cvt_pk_bf16_f32 v159, v118, v119
	v_add_f32_e32 v140, v140, v120
	v_add_f32_e32 v151, v151, v121
	v_mfma_f32_32x32x16_bf16 v[64:79], v[178:181], v[162:165], v[64:79]
	v_exp_f32_e32 v128, v128
	v_exp_f32_e32 v129, v129
	v_cvt_pk_bf16_f32 v160, v120, v121
	v_cvt_pk_bf16_f32 v161, v122, v123
	v_add_f32_e32 v140, v140, v122
	v_add_f32_e32 v151, v151, v123
	v_mfma_f32_32x32x16_bf16 v[0:15], v[186:189], v[162:165], v[0:15]
	v_exp_f32_e32 v130, v130
	v_exp_f32_e32 v131, v131
	v_add_f32_e32 v140, v140, v124
	v_add_f32_e32 v151, v151, v125
	v_add_f32_e32 v140, v140, v126
	v_add_f32_e32 v151, v151, v127
	v_add_f32_e32 v140, v140, v128
	v_add_f32_e32 v151, v151, v129
	v_cvt_pk_bf16_f32 v162, v124, v125
	v_cvt_pk_bf16_f32 v163, v126, v127
	v_cvt_pk_bf16_f32 v164, v128, v129
	v_add_f32_e32 v140, v140, v130
	v_add_f32_e32 v151, v151, v131
	v_cvt_pk_bf16_f32 v165, v130, v131
	s_waitcnt lgkmcnt(0)
	v_mfma_f32_32x32x16_bf16 v[116:131], v[166:169], v[38:41], v[48:63]
	v_exp_f32_e32 v96, v96
	v_exp_f32_e32 v97, v97
	v_exp_f32_e32 v98, v98
	v_exp_f32_e32 v99, v99
	v_mfma_f32_32x32x16_bf16 v[116:131], v[170:173], v[34:37], v[116:131]
	v_exp_f32_e32 v100, v100
	v_exp_f32_e32 v101, v101
	v_exp_f32_e32 v102, v102
	v_exp_f32_e32 v103, v103
	ds_read_b128 v[166:169], v146 offset:16384
	ds_read_b128 v[170:173], v147 offset:16384
	v_mfma_f32_32x32x16_bf16 v[80:95], v[174:177], v[158:161], v[80:95]
	v_exp_f32_e32 v104, v104
	v_exp_f32_e32 v105, v105
	v_add_f32_e32 v141, v141, v96
	v_add_f32_e32 v150, v150, v97
	v_add_f32_e32 v141, v141, v98
	v_add_f32_e32 v150, v150, v99
	v_mfma_f32_32x32x16_bf16 v[16:31], v[182:185], v[158:161], v[16:31]
	v_exp_f32_e32 v106, v106
	v_exp_f32_e32 v107, v107
	v_cvt_pk_bf16_f32 v158, v96, v97
	v_cvt_pk_bf16_f32 v159, v98, v99
	v_add_f32_e32 v141, v141, v100
	v_add_f32_e32 v150, v150, v101
	v_mfma_f32_32x32x16_bf16 v[80:95], v[178:181], v[162:165], v[80:95]
	v_exp_f32_e32 v108, v108
	v_exp_f32_e32 v109, v109
	v_cvt_pk_bf16_f32 v160, v100, v101
	v_cvt_pk_bf16_f32 v161, v102, v103
	v_add_f32_e32 v141, v141, v102
	v_add_f32_e32 v150, v150, v103
	v_mfma_f32_32x32x16_bf16 v[16:31], v[186:189], v[162:165], v[16:31]
	ds_read_b128 v[174:177], v148 offset:8192
	ds_read_b128 v[178:181], v149 offset:8192
	ds_read_b128 v[182:185], v148 offset:12288
	ds_read_b128 v[186:189], v149 offset:12288
	v_exp_f32_e32 v110, v110
	v_exp_f32_e32 v111, v111
	v_add_f32_e32 v141, v141, v104
	v_add_f32_e32 v150, v150, v105
	v_add_f32_e32 v141, v141, v106
	v_add_f32_e32 v150, v150, v107
	v_add_f32_e32 v141, v141, v108
	v_add_f32_e32 v150, v150, v109
	v_cvt_pk_bf16_f32 v162, v104, v105
	v_cvt_pk_bf16_f32 v163, v106, v107
	v_cvt_pk_bf16_f32 v164, v108, v109
	v_add_f32_e32 v141, v141, v110
	v_add_f32_e32 v150, v150, v111
	v_cvt_pk_bf16_f32 v165, v110, v111
	s_waitcnt lgkmcnt(4)
; DI float ex2(float x) { return __builtin_amdgcn_exp2f(x); }
; #define MFMA32(a, b, c) __builtin_amdgcn_mfma_f32_32x32x16_bf16((a), (b), (c), 0, 0, 0)
; template <int MODE>
; DI void attn_unit(unsigned char* lds, const AttnParams& ap, int b, int h, int qb, int tid) {
;     ...
;   for (int n = 0; n < ntiles; n += NCH) {
;     const int jb = (MODE == 2) ? jhi - n : jlo + n;
;     __syncthreads();
;     if (MODE == 2 && D_EARLY) { int alld = 1;
; #pragma unroll
;       for (int w = 0; w < 8; ++w) alld &= flags[w];
;       if (alld) break; }
; #pragma unroll
;     for (int c = 0; c < NCH; ++c) { *(u32x4*)(Ks0 + (c * 64 + lrow) * 72 + 8 * lch) = kreg[c]; *(u32x4*)(Vs0 + (c * 64 + lrow) * 72 + 8 * lch) = vreg[c]; }
;     __syncthreads();
;     if (n + NCH < ntiles) {
; #pragma unroll
;       for (int c = 0; c < NCH; ++c) { const int jn = (MODE == 2) ? jb - NCH - c : jb + NCH + c; kreg[c] = *(const u32x4*)(kg + (size_t)jn * 64 * PLD); vreg[c] = *(const u32x4*)(vg + (size_t)jn * 4096); } }
;     ...
;       for (int kh = 0; kh < 2; ++kh) {
;         const bf16_t* kb = Ks + (32 * kh + r32) * 72 + 8 * hi;
;         bf16x8 p0[2], p1[2];
;         { f32x16 s0 = splat16(ap.negM);
;           s0 = MFMA32(*(const bf16x8*)(kb), qf[0], s0); s0 = MFMA32(*(const bf16x8*)(kb + 16), qf[1], s0);
; #pragma unroll
;           for (int i = 0; i < 16; ++i) { s0[i] = ex2(s0[i]); l0 += s0[i]; }
;           p0[0] = pack8(s0, 0); p0[1] = pack8(s0, 1); }
;         { f32x16 s1 = splat16(ap.negM);
;           s1 = MFMA32(*(const bf16x8*)(kb + 32), qf[2], s1); s1 = MFMA32(*(const bf16x8*)(kb + 48), qf[3], s1);
; #pragma unroll
;           for (int i = 0; i < 16; ++i) { s1[i] = ex2(s1[i]); l1 += s1[i]; }
;           p1[0] = pack8(s1, 0); p1[1] = pack8(s1, 1); }
; #pragma unroll
;         for (int kk = 0; kk < 2; ++kk) {
; #pragma unroll
;           for (int eb = 0; eb < 2; ++eb) { const bf16_t* vb = Vs + (32 * eb + r32) * 72 + 32 * kh + 16 * kk + 8 * hi; const bf16x8 vf = *(const bf16x8*)vb;
;             O0[eb] = MFMA32(vf, p0[kk], O0[eb]); O1[eb] = MFMA32(vf, p1[kk], O1[eb]); } }
	v_mfma_f32_32x32x16_bf16 v[96:111], v[166:169], v[112:115], v[48:63]
	v_exp_f32_e32 v116, v116
	v_exp_f32_e32 v117, v117
	v_exp_f32_e32 v118, v118
	v_exp_f32_e32 v119, v119
	v_mfma_f32_32x32x16_bf16 v[96:111], v[170:173], v[42:45], v[96:111]
	v_exp_f32_e32 v120, v120
	v_exp_f32_e32 v121, v121
	v_exp_f32_e32 v122, v122
	v_exp_f32_e32 v123, v123
	ds_read_b128 v[166:169], v148 offset:16384
	ds_read_b128 v[170:173], v149 offset:16384
	s_waitcnt lgkmcnt(2)
	v_mfma_f32_32x32x16_bf16 v[64:79], v[174:177], v[158:161], v[64:79]
	v_exp_f32_e32 v124, v124
	v_exp_f32_e32 v125, v125
	v_add_f32_e32 v140, v140, v116
	v_add_f32_e32 v151, v151, v117
	v_add_f32_e32 v140, v140, v118
	v_add_f32_e32 v151, v151, v119
	v_mfma_f32_32x32x16_bf16 v[0:15], v[182:185], v[158:161], v[0:15]
	v_exp_f32_e32 v126, v126
	v_exp_f32_e32 v127, v127
	v_cvt_pk_bf16_f32 v158, v116, v117
	v_cvt_pk_bf16_f32 v159, v118, v119
	v_add_f32_e32 v140, v140, v120
	v_add_f32_e32 v151, v151, v121
	v_mfma_f32_32x32x16_bf16 v[64:79], v[178:181], v[162:165], v[64:79]
	v_exp_f32_e32 v128, v128
	v_exp_f32_e32 v129, v129
	v_cvt_pk_bf16_f32 v160, v120, v121
	v_cvt_pk_bf16_f32 v161, v122, v123
	v_add_f32_e32 v140, v140, v122
	v_add_f32_e32 v151, v151, v123
	v_mfma_f32_32x32x16_bf16 v[0:15], v[186:189], v[162:165], v[0:15]
	v_exp_f32_e32 v130, v130
	v_exp_f32_e32 v131, v131
	v_add_f32_e32 v140, v140, v124
	v_add_f32_e32 v151, v151, v125
	v_add_f32_e32 v140, v140, v126
	v_add_f32_e32 v151, v151, v127
	v_add_f32_e32 v140, v140, v128
	v_add_f32_e32 v151, v151, v129
	v_cvt_pk_bf16_f32 v162, v124, v125
	v_cvt_pk_bf16_f32 v163, v126, v127
	v_cvt_pk_bf16_f32 v164, v128, v129
	v_add_f32_e32 v140, v140, v130
	v_add_f32_e32 v151, v151, v131
	v_cvt_pk_bf16_f32 v165, v130, v131
	s_waitcnt vmcnt(0) lgkmcnt(0)
	s_barrier
	s_cmp_le_u32 s4, s5
	s_cbranch_scc1 .Lc_tile_ph1
	s_mov_b32 s9, 1
	s_branch .Lc_drain
.Lc_tile_ph1:
	s_add_i32 m0, s0, 0
	s_add_i32 s4, s4, 1
	global_load_lds_dwordx4 v32, s[2:3]
	s_add_i32 m0, s0, 8192
	s_add_u32 s2, s2, 0x68800
	s_addc_u32 s3, s3, 0
	global_load_lds_dwordx4 v157, s[10:11]
	s_add_u32 s10, s10, 0x2000
	s_addc_u32 s11, s11, 0
	s_waitcnt lgkmcnt(0)
	v_mfma_f32_32x32x16_bf16 v[116:131], v[166:169], v[38:41], v[48:63]
	v_exp_f32_e32 v96, v96
	v_exp_f32_e32 v97, v97
	v_exp_f32_e32 v98, v98
	v_exp_f32_e32 v99, v99
	v_mfma_f32_32x32x16_bf16 v[116:131], v[170:173], v[34:37], v[116:131]
	v_exp_f32_e32 v100, v100
	v_exp_f32_e32 v101, v101
	v_exp_f32_e32 v102, v102
	v_exp_f32_e32 v103, v103
	ds_read_b128 v[166:169], v146 offset:20480
	ds_read_b128 v[170:173], v147 offset:20480
	v_mfma_f32_32x32x16_bf16 v[80:95], v[174:177], v[158:161], v[80:95]
	v_exp_f32_e32 v104, v104
	v_exp_f32_e32 v105, v105
	v_add_f32_e32 v141, v141, v96
	v_add_f32_e32 v150, v150, v97
	v_add_f32_e32 v141, v141, v98
	v_add_f32_e32 v150, v150, v99
	v_mfma_f32_32x32x16_bf16 v[16:31], v[182:185], v[158:161], v[16:31]
	v_exp_f32_e32 v106, v106
	v_exp_f32_e32 v107, v107
	v_cvt_pk_bf16_f32 v158, v96, v97
	v_cvt_pk_bf16_f32 v159, v98, v99
	v_add_f32_e32 v141, v141, v100
	v_add_f32_e32 v150, v150, v101
	v_mfma_f32_32x32x16_bf16 v[80:95], v[178:181], v[162:165], v[80:95]
	v_exp_f32_e32 v108, v108
	v_exp_f32_e32 v109, v109
	v_cvt_pk_bf16_f32 v160, v100, v101
	v_cvt_pk_bf16_f32 v161, v102, v103
	v_add_f32_e32 v141, v141, v102
	v_add_f32_e32 v150, v150, v103
	v_mfma_f32_32x32x16_bf16 v[16:31], v[186:189], v[162:165], v[16:31]
	ds_read_b128 v[174:177], v146 offset:24576
	ds_read_b128 v[178:181], v147 offset:24576
	ds_read_b128 v[182:185], v146 offset:28672
	ds_read_b128 v[186:189], v147 offset:28672
	v_exp_f32_e32 v110, v110
	v_exp_f32_e32 v111, v111
	v_add_f32_e32 v141, v141, v104
	v_add_f32_e32 v150, v150, v105
	v_add_f32_e32 v141, v141, v106
	v_add_f32_e32 v150, v150, v107
	v_add_f32_e32 v141, v141, v108
	v_add_f32_e32 v150, v150, v109
	v_cvt_pk_bf16_f32 v162, v104, v105
	v_cvt_pk_bf16_f32 v163, v106, v107
	v_cvt_pk_bf16_f32 v164, v108, v109
	v_add_f32_e32 v141, v141, v110
	v_add_f32_e32 v150, v150, v111
	v_cvt_pk_bf16_f32 v165, v110, v111
	s_waitcnt lgkmcnt(4)
	v_mfma_f32_32x32x16_bf16 v[96:111], v[166:169], v[112:115], v[48:63]
	v_exp_f32_e32 v116, v116
	v_exp_f32_e32 v117, v117
	v_exp_f32_e32 v118, v118
	v_exp_f32_e32 v119, v119
	v_mfma_f32_32x32x16_bf16 v[96:111], v[170:173], v[42:45], v[96:111]
	v_exp_f32_e32 v120, v120
	v_exp_f32_e32 v121, v121
	v_exp_f32_e32 v122, v122
	v_exp_f32_e32 v123, v123
	ds_read_b128 v[166:169], v148 offset:20480
	ds_read_b128 v[170:173], v149 offset:20480
	s_waitcnt lgkmcnt(2)
	v_mfma_f32_32x32x16_bf16 v[64:79], v[174:177], v[158:161], v[64:79]
	v_exp_f32_e32 v124, v124
	v_exp_f32_e32 v125, v125
	v_add_f32_e32 v140, v140, v116
	v_add_f32_e32 v151, v151, v117
	v_add_f32_e32 v140, v140, v118
	v_add_f32_e32 v151, v151, v119
	v_mfma_f32_32x32x16_bf16 v[0:15], v[182:185], v[158:161], v[0:15]
	v_exp_f32_e32 v126, v126
	v_exp_f32_e32 v127, v127
	v_cvt_pk_bf16_f32 v158, v116, v117
	v_cvt_pk_bf16_f32 v159, v118, v119
	v_add_f32_e32 v140, v140, v120
	v_add_f32_e32 v151, v151, v121
	v_mfma_f32_32x32x16_bf16 v[64:79], v[178:181], v[162:165], v[64:79]
	v_exp_f32_e32 v128, v128
	v_exp_f32_e32 v129, v129
	v_cvt_pk_bf16_f32 v160, v120, v121
	v_cvt_pk_bf16_f32 v161, v122, v123
	v_add_f32_e32 v140, v140, v122
	v_add_f32_e32 v151, v151, v123
	v_mfma_f32_32x32x16_bf16 v[0:15], v[186:189], v[162:165], v[0:15]
	v_exp_f32_e32 v130, v130
	v_exp_f32_e32 v131, v131
	v_add_f32_e32 v140, v140, v124
	v_add_f32_e32 v151, v151, v125
	v_add_f32_e32 v140, v140, v126
	v_add_f32_e32 v151, v151, v127
	v_add_f32_e32 v140, v140, v128
	v_add_f32_e32 v151, v151, v129
	v_cvt_pk_bf16_f32 v162, v124, v125
	v_cvt_pk_bf16_f32 v163, v126, v127
	v_cvt_pk_bf16_f32 v164, v128, v129
	v_add_f32_e32 v140, v140, v130
	v_add_f32_e32 v151, v151, v131
	v_cvt_pk_bf16_f32 v165, v130, v131
	s_waitcnt lgkmcnt(0)
; DI float ex2(float x) { return __builtin_amdgcn_exp2f(x); }
; #define MFMA32(a, b, c) __builtin_amdgcn_mfma_f32_32x32x16_bf16((a), (b), (c), 0, 0, 0)
; template <int MODE>
; DI void attn_unit(unsigned char* lds, const AttnParams& ap, int b, int h, int qb, int tid) {
;     ...
;   for (int n = 0; n < ntiles; n += NCH) {
;     const int jb = (MODE == 2) ? jhi - n : jlo + n;
;     __syncthreads();
;     if (MODE == 2 && D_EARLY) { int alld = 1;
; #pragma unroll
;       for (int w = 0; w < 8; ++w) alld &= flags[w];
;       if (alld) break; }
; #pragma unroll
;     for (int c = 0; c < NCH; ++c) { *(u32x4*)(Ks0 + (c * 64 + lrow) * 72 + 8 * lch) = kreg[c]; *(u32x4*)(Vs0 + (c * 64 + lrow) * 72 + 8 * lch) = vreg[c]; }
;     __syncthreads();
;     if (n + NCH < ntiles) {
; #pragma unroll
;       for (int c = 0; c < NCH; ++c) { const int jn = (MODE == 2) ? jb - NCH - c : jb + NCH + c; kreg[c] = *(const u32x4*)(kg + (size_t)jn * 64 * PLD); vreg[c] = *(const u32x4*)(vg + (size_t)jn * 4096); } }
;     ...
;       for (int kh = 0; kh < 2; ++kh) {
;         const bf16_t* kb = Ks + (32 * kh + r32) * 72 + 8 * hi;
;         bf16x8 p0[2], p1[2];
;         { f32x16 s0 = splat16(ap.negM);
;           s0 = MFMA32(*(const bf16x8*)(kb), qf[0], s0); s0 = MFMA32(*(const bf16x8*)(kb + 16), qf[1], s0);
; #pragma unroll
;           for (int i = 0; i < 16; ++i) { s0[i] = ex2(s0[i]); l0 += s0[i]; }
;           p0[0] = pack8(s0, 0); p0[1] = pack8(s0, 1); }
;         { f32x16 s1 = splat16(ap.negM);
;           s1 = MFMA32(*(const bf16x8*)(kb + 32), qf[2], s1); s1 = MFMA32(*(const bf16x8*)(kb + 48), qf[3], s1);
; #pragma unroll
;           for (int i = 0; i < 16; ++i) { s1[i] = ex2(s1[i]); l1 += s1[i]; }
;           p1[0] = pack8(s1, 0); p1[1] = pack8(s1, 1); }
; #pragma unroll
;         for (int kk = 0; kk < 2; ++kk) {
; #pragma unroll
;           for (int eb = 0; eb < 2; ++eb) { const bf16_t* vb = Vs + (32 * eb + r32) * 72 + 32 * kh + 16 * kk + 8 * hi; const bf16x8 vf = *(const bf16x8*)vb;
;             O0[eb] = MFMA32(vf, p0[kk], O0[eb]); O1[eb] = MFMA32(vf, p1[kk], O1[eb]); } }
	v_mfma_f32_32x32x16_bf16 v[116:131], v[166:169], v[38:41], v[48:63]
	v_exp_f32_e32 v96, v96
	v_exp_f32_e32 v97, v97
	v_exp_f32_e32 v98, v98
	v_exp_f32_e32 v99, v99
	v_mfma_f32_32x32x16_bf16 v[116:131], v[170:173], v[34:37], v[116:131]
	v_exp_f32_e32 v100, v100
	v_exp_f32_e32 v101, v101
	v_exp_f32_e32 v102, v102
	v_exp_f32_e32 v103, v103
	ds_read_b128 v[166:169], v146 offset:32768
	ds_read_b128 v[170:173], v147 offset:32768
	v_mfma_f32_32x32x16_bf16 v[80:95], v[174:177], v[158:161], v[80:95]
	v_exp_f32_e32 v104, v104
	v_exp_f32_e32 v105, v105
	v_add_f32_e32 v141, v141, v96
	v_add_f32_e32 v150, v150, v97
	v_add_f32_e32 v141, v141, v98
	v_add_f32_e32 v150, v150, v99
	v_mfma_f32_32x32x16_bf16 v[16:31], v[182:185], v[158:161], v[16:31]
	v_exp_f32_e32 v106, v106
	v_exp_f32_e32 v107, v107
	v_cvt_pk_bf16_f32 v158, v96, v97
	v_cvt_pk_bf16_f32 v159, v98, v99
	v_add_f32_e32 v141, v141, v100
	v_add_f32_e32 v150, v150, v101
	v_mfma_f32_32x32x16_bf16 v[80:95], v[178:181], v[162:165], v[80:95]
	v_exp_f32_e32 v108, v108
	v_exp_f32_e32 v109, v109
	v_cvt_pk_bf16_f32 v160, v100, v101
	v_cvt_pk_bf16_f32 v161, v102, v103
	v_add_f32_e32 v141, v141, v102
	v_add_f32_e32 v150, v150, v103
	v_mfma_f32_32x32x16_bf16 v[16:31], v[186:189], v[162:165], v[16:31]
	ds_read_b128 v[174:177], v148 offset:24576
	ds_read_b128 v[178:181], v149 offset:24576
	ds_read_b128 v[182:185], v148 offset:28672
	ds_read_b128 v[186:189], v149 offset:28672
	v_exp_f32_e32 v110, v110
	v_exp_f32_e32 v111, v111
	v_add_f32_e32 v141, v141, v104
	v_add_f32_e32 v150, v150, v105
	v_add_f32_e32 v141, v141, v106
	v_add_f32_e32 v150, v150, v107
	v_add_f32_e32 v141, v141, v108
	v_add_f32_e32 v150, v150, v109
	v_cvt_pk_bf16_f32 v162, v104, v105
	v_cvt_pk_bf16_f32 v163, v106, v107
	v_cvt_pk_bf16_f32 v164, v108, v109
	v_add_f32_e32 v141, v141, v110
	v_add_f32_e32 v150, v150, v111
	v_cvt_pk_bf16_f32 v165, v110, v111
	s_waitcnt lgkmcnt(4)
	v_mfma_f32_32x32x16_bf16 v[96:111], v[166:169], v[112:115], v[48:63]
	v_exp_f32_e32 v116, v116
	v_exp_f32_e32 v117, v117
	v_exp_f32_e32 v118, v118
	v_exp_f32_e32 v119, v119
	v_mfma_f32_32x32x16_bf16 v[96:111], v[170:173], v[42:45], v[96:111]
	v_exp_f32_e32 v120, v120
	v_exp_f32_e32 v121, v121
	v_exp_f32_e32 v122, v122
	v_exp_f32_e32 v123, v123
	ds_read_b128 v[166:169], v148 offset:32768
	ds_read_b128 v[170:173], v149 offset:32768
	s_waitcnt lgkmcnt(2)
	v_mfma_f32_32x32x16_bf16 v[64:79], v[174:177], v[158:161], v[64:79]
	v_exp_f32_e32 v124, v124
	v_exp_f32_e32 v125, v125
	v_add_f32_e32 v140, v140, v116
	v_add_f32_e32 v151, v151, v117
	v_add_f32_e32 v140, v140, v118
	v_add_f32_e32 v151, v151, v119
	v_mfma_f32_32x32x16_bf16 v[0:15], v[182:185], v[158:161], v[0:15]
	v_exp_f32_e32 v126, v126
	v_exp_f32_e32 v127, v127
	v_cvt_pk_bf16_f32 v158, v116, v117
	v_cvt_pk_bf16_f32 v159, v118, v119
	v_add_f32_e32 v140, v140, v120
	v_add_f32_e32 v151, v151, v121
	v_mfma_f32_32x32x16_bf16 v[64:79], v[178:181], v[162:165], v[64:79]
	v_exp_f32_e32 v128, v128
	v_exp_f32_e32 v129, v129
	v_cvt_pk_bf16_f32 v160, v120, v121
	v_cvt_pk_bf16_f32 v161, v122, v123
	v_add_f32_e32 v140, v140, v122
	v_add_f32_e32 v151, v151, v123
	v_mfma_f32_32x32x16_bf16 v[0:15], v[186:189], v[162:165], v[0:15]
	v_exp_f32_e32 v130, v130
	v_exp_f32_e32 v131, v131
	v_add_f32_e32 v140, v140, v124
	v_add_f32_e32 v151, v151, v125
	v_add_f32_e32 v140, v140, v126
	v_add_f32_e32 v151, v151, v127
	v_add_f32_e32 v140, v140, v128
	v_add_f32_e32 v151, v151, v129
	v_cvt_pk_bf16_f32 v162, v124, v125
	v_cvt_pk_bf16_f32 v163, v126, v127
	v_cvt_pk_bf16_f32 v164, v128, v129
	v_add_f32_e32 v140, v140, v130
	v_add_f32_e32 v151, v151, v131
	v_cvt_pk_bf16_f32 v165, v130, v131
	s_waitcnt vmcnt(0) lgkmcnt(0)
	s_barrier
	s_cmp_le_u32 s4, s5
	s_cbranch_scc1 .Lc_tile_ph2
	s_mov_b32 s9, 2
	s_branch .Lc_drain
.Lc_tile_ph2:
	s_add_i32 m0, s0, 16384
	s_add_i32 s4, s4, 1
	global_load_lds_dwordx4 v32, s[2:3]
	s_add_i32 m0, s0, 24576
	s_add_u32 s2, s2, 0x68800
	s_addc_u32 s3, s3, 0
	global_load_lds_dwordx4 v157, s[10:11]
	s_add_u32 s10, s10, 0x2000
	s_addc_u32 s11, s11, 0
	s_waitcnt lgkmcnt(0)
	v_mfma_f32_32x32x16_bf16 v[116:131], v[166:169], v[38:41], v[48:63]
	v_exp_f32_e32 v96, v96
	v_exp_f32_e32 v97, v97
	v_exp_f32_e32 v98, v98
	v_exp_f32_e32 v99, v99
	v_mfma_f32_32x32x16_bf16 v[116:131], v[170:173], v[34:37], v[116:131]
	v_exp_f32_e32 v100, v100
	v_exp_f32_e32 v101, v101
	v_exp_f32_e32 v102, v102
	v_exp_f32_e32 v103, v103
	ds_read_b128 v[166:169], v146 offset:36864
	ds_read_b128 v[170:173], v147 offset:36864
	v_mfma_f32_32x32x16_bf16 v[80:95], v[174:177], v[158:161], v[80:95]
	v_exp_f32_e32 v104, v104
	v_exp_f32_e32 v105, v105
	v_add_f32_e32 v141, v141, v96
	v_add_f32_e32 v150, v150, v97
	v_add_f32_e32 v141, v141, v98
	v_add_f32_e32 v150, v150, v99
	v_mfma_f32_32x32x16_bf16 v[16:31], v[182:185], v[158:161], v[16:31]
	v_exp_f32_e32 v106, v106
	v_exp_f32_e32 v107, v107
	v_cvt_pk_bf16_f32 v158, v96, v97
	v_cvt_pk_bf16_f32 v159, v98, v99
	v_add_f32_e32 v141, v141, v100
	v_add_f32_e32 v150, v150, v101
	v_mfma_f32_32x32x16_bf16 v[80:95], v[178:181], v[162:165], v[80:95]
	v_exp_f32_e32 v108, v108
	v_exp_f32_e32 v109, v109
	v_cvt_pk_bf16_f32 v160, v100, v101
	v_cvt_pk_bf16_f32 v161, v102, v103
	v_add_f32_e32 v141, v141, v102
	v_add_f32_e32 v150, v150, v103
	v_mfma_f32_32x32x16_bf16 v[16:31], v[186:189], v[162:165], v[16:31]
	ds_read_b128 v[174:177], v146 offset:40960
	ds_read_b128 v[178:181], v147 offset:40960
	ds_read_b128 v[182:185], v146 offset:45056
	ds_read_b128 v[186:189], v147 offset:45056
	v_exp_f32_e32 v110, v110
	v_exp_f32_e32 v111, v111
	v_add_f32_e32 v141, v141, v104
	v_add_f32_e32 v150, v150, v105
	v_add_f32_e32 v141, v141, v106
	v_add_f32_e32 v150, v150, v107
	v_add_f32_e32 v141, v141, v108
	v_add_f32_e32 v150, v150, v109
	v_cvt_pk_bf16_f32 v162, v104, v105
	v_cvt_pk_bf16_f32 v163, v106, v107
	v_cvt_pk_bf16_f32 v164, v108, v109
	v_add_f32_e32 v141, v141, v110
	v_add_f32_e32 v150, v150, v111
	v_cvt_pk_bf16_f32 v165, v110, v111
	s_waitcnt lgkmcnt(4)
; DI float ex2(float x) { return __builtin_amdgcn_exp2f(x); }
; #define MFMA32(a, b, c) __builtin_amdgcn_mfma_f32_32x32x16_bf16((a), (b), (c), 0, 0, 0)
; template <int MODE>
; DI void attn_unit(unsigned char* lds, const AttnParams& ap, int b, int h, int qb, int tid) {
;     ...
;   for (int n = 0; n < ntiles; n += NCH) {
;     const int jb = (MODE == 2) ? jhi - n : jlo + n;
;     __syncthreads();
;     if (MODE == 2 && D_EARLY) { int alld = 1;
; #pragma unroll
;       for (int w = 0; w < 8; ++w) alld &= flags[w];
;       if (alld) break; }
; #pragma unroll
;     for (int c = 0; c < NCH; ++c) { *(u32x4*)(Ks0 + (c * 64 + lrow) * 72 + 8 * lch) = kreg[c]; *(u32x4*)(Vs0 + (c * 64 + lrow) * 72 + 8 * lch) = vreg[c]; }
;     __syncthreads();
;     if (n + NCH < ntiles) {
; #pragma unroll
;       for (int c = 0; c < NCH; ++c) { const int jn = (MODE == 2) ? jb - NCH - c : jb + NCH + c; kreg[c] = *(const u32x4*)(kg + (size_t)jn * 64 * PLD); vreg[c] = *(const u32x4*)(vg + (size_t)jn * 4096); } }
;     ...
;       for (int kh = 0; kh < 2; ++kh) {
;         const bf16_t* kb = Ks + (32 * kh + r32) * 72 + 8 * hi;
;         bf16x8 p0[2], p1[2];
;         { f32x16 s0 = splat16(ap.negM);
;           s0 = MFMA32(*(const bf16x8*)(kb), qf[0], s0); s0 = MFMA32(*(const bf16x8*)(kb + 16), qf[1], s0);
; #pragma unroll
;           for (int i = 0; i < 16; ++i) { s0[i] = ex2(s0[i]); l0 += s0[i]; }
;           p0[0] = pack8(s0, 0); p0[1] = pack8(s0, 1); }
;         { f32x16 s1 = splat16(ap.negM);
;           s1 = MFMA32(*(const bf16x8*)(kb + 32), qf[2], s1); s1 = MFMA32(*(const bf16x8*)(kb + 48), qf[3], s1);
; #pragma unroll
;           for (int i = 0; i < 16; ++i) { s1[i] = ex2(s1[i]); l1 += s1[i]; }
;           p1[0] = pack8(s1, 0); p1[1] = pack8(s1, 1); }
; #pragma unroll
;         for (int kk = 0; kk < 2; ++kk) {
; #pragma unroll
;           for (int eb = 0; eb < 2; ++eb) { const bf16_t* vb = Vs + (32 * eb + r32) * 72 + 32 * kh + 16 * kk + 8 * hi; const bf16x8 vf = *(const bf16x8*)vb;
;             O0[eb] = MFMA32(vf, p0[kk], O0[eb]); O1[eb] = MFMA32(vf, p1[kk], O1[eb]); } }
	v_mfma_f32_32x32x16_bf16 v[96:111], v[166:169], v[112:115], v[48:63]
	v_exp_f32_e32 v116, v116
	v_exp_f32_e32 v117, v117
	v_exp_f32_e32 v118, v118
	v_exp_f32_e32 v119, v119
	v_mfma_f32_32x32x16_bf16 v[96:111], v[170:173], v[42:45], v[96:111]
	v_exp_f32_e32 v120, v120
	v_exp_f32_e32 v121, v121
	v_exp_f32_e32 v122, v122
	v_exp_f32_e32 v123, v123
	ds_read_b128 v[166:169], v148 offset:36864
	ds_read_b128 v[170:173], v149 offset:36864
	s_waitcnt lgkmcnt(2)
	v_mfma_f32_32x32x16_bf16 v[64:79], v[174:177], v[158:161], v[64:79]
	v_exp_f32_e32 v124, v124
	v_exp_f32_e32 v125, v125
	v_add_f32_e32 v140, v140, v116
	v_add_f32_e32 v151, v151, v117
	v_add_f32_e32 v140, v140, v118
	v_add_f32_e32 v151, v151, v119
	v_mfma_f32_32x32x16_bf16 v[0:15], v[182:185], v[158:161], v[0:15]
	v_exp_f32_e32 v126, v126
	v_exp_f32_e32 v127, v127
	v_cvt_pk_bf16_f32 v158, v116, v117
	v_cvt_pk_bf16_f32 v159, v118, v119
	v_add_f32_e32 v140, v140, v120
	v_add_f32_e32 v151, v151, v121
	v_mfma_f32_32x32x16_bf16 v[64:79], v[178:181], v[162:165], v[64:79]
	v_exp_f32_e32 v128, v128
	v_exp_f32_e32 v129, v129
	v_cvt_pk_bf16_f32 v160, v120, v121
	v_cvt_pk_bf16_f32 v161, v122, v123
	v_add_f32_e32 v140, v140, v122
	v_add_f32_e32 v151, v151, v123
	v_mfma_f32_32x32x16_bf16 v[0:15], v[186:189], v[162:165], v[0:15]
	v_exp_f32_e32 v130, v130
	v_exp_f32_e32 v131, v131
	v_add_f32_e32 v140, v140, v124
	v_add_f32_e32 v151, v151, v125
	v_add_f32_e32 v140, v140, v126
	v_add_f32_e32 v151, v151, v127
	v_add_f32_e32 v140, v140, v128
	v_add_f32_e32 v151, v151, v129
	v_cvt_pk_bf16_f32 v162, v124, v125
	v_cvt_pk_bf16_f32 v163, v126, v127
	v_cvt_pk_bf16_f32 v164, v128, v129
	v_add_f32_e32 v140, v140, v130
	v_add_f32_e32 v151, v151, v131
	v_cvt_pk_bf16_f32 v165, v130, v131
	s_waitcnt lgkmcnt(0)
	v_mfma_f32_32x32x16_bf16 v[116:131], v[166:169], v[38:41], v[48:63]
	v_exp_f32_e32 v96, v96
	v_exp_f32_e32 v97, v97
	v_exp_f32_e32 v98, v98
	v_exp_f32_e32 v99, v99
	v_mfma_f32_32x32x16_bf16 v[116:131], v[170:173], v[34:37], v[116:131]
	v_exp_f32_e32 v100, v100
	v_exp_f32_e32 v101, v101
	v_exp_f32_e32 v102, v102
	v_exp_f32_e32 v103, v103
	ds_read_b128 v[166:169], v146
	ds_read_b128 v[170:173], v147
	v_mfma_f32_32x32x16_bf16 v[80:95], v[174:177], v[158:161], v[80:95]
	v_exp_f32_e32 v104, v104
	v_exp_f32_e32 v105, v105
	v_add_f32_e32 v141, v141, v96
	v_add_f32_e32 v150, v150, v97
	v_add_f32_e32 v141, v141, v98
	v_add_f32_e32 v150, v150, v99
	v_mfma_f32_32x32x16_bf16 v[16:31], v[182:185], v[158:161], v[16:31]
	v_exp_f32_e32 v106, v106
	v_exp_f32_e32 v107, v107
	v_cvt_pk_bf16_f32 v158, v96, v97
	v_cvt_pk_bf16_f32 v159, v98, v99
	v_add_f32_e32 v141, v141, v100
	v_add_f32_e32 v150, v150, v101
	v_mfma_f32_32x32x16_bf16 v[80:95], v[178:181], v[162:165], v[80:95]
	v_exp_f32_e32 v108, v108
	v_exp_f32_e32 v109, v109
	v_cvt_pk_bf16_f32 v160, v100, v101
	v_cvt_pk_bf16_f32 v161, v102, v103
	v_add_f32_e32 v141, v141, v102
	v_add_f32_e32 v150, v150, v103
	v_mfma_f32_32x32x16_bf16 v[16:31], v[186:189], v[162:165], v[16:31]
	ds_read_b128 v[174:177], v148 offset:40960
	ds_read_b128 v[178:181], v149 offset:40960
	ds_read_b128 v[182:185], v148 offset:45056
	ds_read_b128 v[186:189], v149 offset:45056
	v_exp_f32_e32 v110, v110
	v_exp_f32_e32 v111, v111
	v_add_f32_e32 v141, v141, v104
	v_add_f32_e32 v150, v150, v105
	v_add_f32_e32 v141, v141, v106
	v_add_f32_e32 v150, v150, v107
	v_add_f32_e32 v141, v141, v108
	v_add_f32_e32 v150, v150, v109
	v_cvt_pk_bf16_f32 v162, v104, v105
	v_cvt_pk_bf16_f32 v163, v106, v107
	v_cvt_pk_bf16_f32 v164, v108, v109
	v_add_f32_e32 v141, v141, v110
	v_add_f32_e32 v150, v150, v111
	v_cvt_pk_bf16_f32 v165, v110, v111
	s_waitcnt lgkmcnt(4)
	v_mfma_f32_32x32x16_bf16 v[96:111], v[166:169], v[112:115], v[48:63]
	v_exp_f32_e32 v116, v116
	v_exp_f32_e32 v117, v117
	v_exp_f32_e32 v118, v118
	v_exp_f32_e32 v119, v119
	v_mfma_f32_32x32x16_bf16 v[96:111], v[170:173], v[42:45], v[96:111]
	v_exp_f32_e32 v120, v120
	v_exp_f32_e32 v121, v121
	v_exp_f32_e32 v122, v122
	v_exp_f32_e32 v123, v123
	ds_read_b128 v[166:169], v148
	ds_read_b128 v[170:173], v149
	s_waitcnt lgkmcnt(2)
	v_mfma_f32_32x32x16_bf16 v[64:79], v[174:177], v[158:161], v[64:79]
	v_exp_f32_e32 v124, v124
	v_exp_f32_e32 v125, v125
	v_add_f32_e32 v140, v140, v116
	v_add_f32_e32 v151, v151, v117
	v_add_f32_e32 v140, v140, v118
	v_add_f32_e32 v151, v151, v119
	v_mfma_f32_32x32x16_bf16 v[0:15], v[182:185], v[158:161], v[0:15]
	v_exp_f32_e32 v126, v126
	v_exp_f32_e32 v127, v127
	v_cvt_pk_bf16_f32 v158, v116, v117
	v_cvt_pk_bf16_f32 v159, v118, v119
	v_add_f32_e32 v140, v140, v120
	v_add_f32_e32 v151, v151, v121
	v_mfma_f32_32x32x16_bf16 v[64:79], v[178:181], v[162:165], v[64:79]
	v_exp_f32_e32 v128, v128
	v_exp_f32_e32 v129, v129
	v_cvt_pk_bf16_f32 v160, v120, v121
	v_cvt_pk_bf16_f32 v161, v122, v123
	v_add_f32_e32 v140, v140, v122
	v_add_f32_e32 v151, v151, v123
	v_mfma_f32_32x32x16_bf16 v[0:15], v[186:189], v[162:165], v[0:15]
	v_exp_f32_e32 v130, v130
	v_exp_f32_e32 v131, v131
	v_add_f32_e32 v140, v140, v124
	v_add_f32_e32 v151, v151, v125
	v_add_f32_e32 v140, v140, v126
	v_add_f32_e32 v151, v151, v127
	v_add_f32_e32 v140, v140, v128
	v_add_f32_e32 v151, v151, v129
	v_cvt_pk_bf16_f32 v162, v124, v125
	v_cvt_pk_bf16_f32 v163, v126, v127
	v_cvt_pk_bf16_f32 v164, v128, v129
	v_add_f32_e32 v140, v140, v130
	v_add_f32_e32 v151, v151, v131
	v_cvt_pk_bf16_f32 v165, v130, v131
	s_waitcnt vmcnt(0) lgkmcnt(0)
	s_barrier
	s_cmp_le_u32 s4, s5
	s_cbranch_scc1 .Lc_tile_ph0
	s_mov_b32 s9, 0

; template <int MODE>
; DI void attn_unit(unsigned char* lds, const AttnParams& ap, int b, int h, int qb, int tid) {
;     ...
;   for (int n = 0; n < ntiles; n += NCH) {
;     const int jb = (MODE == 2) ? jhi - n : jlo + n;
;     __syncthreads();
;     if (MODE == 2 && D_EARLY) { int alld = 1;
; #pragma unroll
;       for (int w = 0; w < 8; ++w) alld &= flags[w];
;       if (alld) break; }
; #pragma unroll
;     for (int c = 0; c < NCH; ++c) { *(u32x4*)(Ks0 + (c * 64 + lrow) * 72 + 8 * lch) = kreg[c]; *(u32x4*)(Vs0 + (c * 64 + lrow) * 72 + 8 * lch) = vreg[c]; }
;     __syncthreads();
;     if (n + NCH < ntiles) {
; #pragma unroll
;       for (int c = 0; c < NCH; ++c) { const int jn = (MODE == 2) ? jb - NCH - c : jb + NCH + c; kreg[c] = *(const u32x4*)(kg + (size_t)jn * 64 * PLD); vreg[c] = *(const u32x4*)(vg + (size_t)jn * 4096); } }
; #pragma unroll
;     for (int c = 0; c < NCH; ++c) {
;     const int j = (MODE == 2) ? jb - c : jb + c;
;     const bf16_t* Ks = Ks0 + c * 64 * 72; const bf16_t* Vs = Vs0 + c * 64 * 72;
;     const bool active = (j <= cw) && (MODE != 0 || j >= cw - 8);
;     if (!active) continue;
.Lc_idle_ph0:
	s_add_i32 m0, s0, 32768
	s_add_i32 s4, s4, 1
	global_load_lds_dwordx4 v32, s[2:3]
	s_add_i32 m0, s0, 40960
	s_add_u32 s2, s2, 0x68800
	s_addc_u32 s3, s3, 0
	global_load_lds_dwordx4 v157, s[10:11]
	s_add_u32 s10, s10, 0x2000
	s_addc_u32 s11, s11, 0
	s_waitcnt vmcnt(0) lgkmcnt(0)
	s_barrier
	s_cmp_gt_u32 s4, s8
	s_cbranch_scc1 .Lc_tiles_done
.Lc_idle_ph1:
	s_add_i32 m0, s0, 0
	s_add_i32 s4, s4, 1
	global_load_lds_dwordx4 v32, s[2:3]
	s_add_i32 m0, s0, 8192
	s_add_u32 s2, s2, 0x68800
	s_addc_u32 s3, s3, 0
	global_load_lds_dwordx4 v157, s[10:11]
	s_add_u32 s10, s10, 0x2000
	s_addc_u32 s11, s11, 0
	s_waitcnt vmcnt(0) lgkmcnt(0)
	s_barrier
	s_cmp_gt_u32 s4, s8
	s_cbranch_scc1 .Lc_tiles_done
.Lc_idle_ph2:
	s_add_i32 m0, s0, 16384
	s_add_i32 s4, s4, 1
	global_load_lds_dwordx4 v32, s[2:3]
	s_add_i32 m0, s0, 24576
	s_add_u32 s2, s2, 0x68800
	s_addc_u32 s3, s3, 0
	global_load_lds_dwordx4 v157, s[10:11]
	s_add_u32 s10, s10, 0x2000
	s_addc_u32 s11, s11, 0
	s_waitcnt vmcnt(0) lgkmcnt(0)
	s_barrier
	s_cmp_gt_u32 s4, s8
	s_cbranch_scc1 .Lc_tiles_done
	s_branch .Lc_idle_ph0
